# first grid barrier: 16 per-XCD counter reads issued together instead of 16 dependent round trips
# speedup vs baseline: 1.0021x; 1.0021x over previous
.LBB0_593:
	s_waitcnt lgkmcnt(0)
	s_mov_b64 s[36:37], -1
	global_load_dword v0, v163, s[10:11] sc1
	global_load_dword v1, v163, s[10:11] offset:256 sc1
	global_load_dword v2, v163, s[10:11] offset:512 sc1
	global_load_dword v3, v163, s[10:11] offset:768 sc1
	global_load_dword v4, v163, s[10:11] offset:1024 sc1
	global_load_dword v5, v163, s[10:11] offset:1280 sc1
	global_load_dword v6, v163, s[10:11] offset:1536 sc1
	global_load_dword v7, v163, s[10:11] offset:1792 sc1
	global_load_dword v8, v163, s[10:11] offset:2048 sc1
	global_load_dword v9, v163, s[10:11] offset:2304 sc1
	global_load_dword v10, v163, s[10:11] offset:2560 sc1
	global_load_dword v11, v163, s[10:11] offset:2816 sc1
	global_load_dword v12, v163, s[10:11] offset:3072 sc1
	global_load_dword v13, v163, s[10:11] offset:3328 sc1
	global_load_dword v14, v163, s[10:11] offset:3584 sc1
	global_load_dword v15, v163, s[10:11] offset:3840 sc1
	s_mov_b64 s[2:3], -1
	s_waitcnt vmcnt(0)
	v_add_u32_e32 v16, v1, v0
	v_add_u32_e32 v16, v16, v2
	v_add_u32_e32 v16, v16, v3
	v_add_u32_e32 v16, v16, v4
	v_add_u32_e32 v16, v16, v5
	v_add_u32_e32 v16, v16, v6
	v_add_u32_e32 v16, v16, v7
	v_add_u32_e32 v16, v16, v8
	v_add_u32_e32 v16, v16, v9
	v_add_u32_e32 v16, v16, v10
	v_add_u32_e32 v16, v16, v11
	v_add_u32_e32 v16, v16, v12
	v_add_u32_e32 v16, v16, v13
	v_add_u32_e32 v16, v16, v14
	v_add_u32_e32 v16, v16, v15
	v_cmp_eq_u32_e32 vcc, s87, v16
	s_cbranch_vccnz .LBB0_592
	s_and_b32 s2, s4, 0xff
	s_cmp_eq_u32 s2, 0
	s_mov_b64 s[2:3], -1
	s_mov_b64 s[38:39], -1
	s_sleep 1
	s_cbranch_scc1 .LBB0_597
	s_and_b64 vcc, exec, s[38:39]
	s_cbranch_vccz .LBB0_592
